# silu gate epilogues: f32 division as reciprocal + exact fma residual correction + div_fixup (no range scaling needed for 1+exp(-x) >= 1)
# speedup vs baseline: 1.1315x; 1.0071x over previous
.LBB0_165:
	ds_read_b128 v[204:207], v138
	ds_read_b128 v[208:211], v138 offset:32
	ds_read_b128 v[212:215], v138 offset:4608
	ds_read_b128 v[216:219], v138 offset:4640
	ds_read_b128 v[220:223], v139 offset:36864
	ds_read_b128 v[224:227], v139 offset:36896
	ds_read_b128 v[228:231], v139 offset:41472
	ds_read_b128 v[232:235], v139 offset:41504
	s_waitcnt vmcnt(15)
	ds_write_b128 v199, v[94:97] offset:18432
	buffer_load_dwordx4 v[94:97], v200, s[44:47], s0 offen
	s_waitcnt lgkmcnt(4)
	v_mfma_f32_32x32x16_bf16 v[50:65], v[204:207], v[220:223], v[50:65]
	s_add_u32 s24, s20, s0
	s_addc_u32 s22, s21, s1
	s_and_b32 s25, s22, 0xffff
	s_waitcnt lgkmcnt(2)
	v_mfma_f32_32x32x16_bf16 v[34:49], v[204:207], v[228:231], v[34:49]
	s_waitcnt vmcnt(15)
	ds_write_b128 v199, v[90:93] offset:55296
	buffer_load_dwordx4 v[90:93], v200, s[24:27], 0 offen
	v_mfma_f32_32x32x16_bf16 v[18:33], v[212:215], v[220:223], v[18:33]
	v_mfma_f32_32x32x16_bf16 v[2:17], v[212:215], v[228:231], v[2:17]
	s_add_i32 s22, s0, 0x11000
	ds_read_b128 v[204:207], v138 offset:64
	ds_read_b128 v[212:215], v138 offset:4672
	ds_read_b128 v[220:223], v139 offset:36928
	ds_read_b128 v[228:231], v139 offset:41536
	s_waitcnt vmcnt(15)
	ds_write_b128 v199, v[86:89] offset:23040
	buffer_load_dwordx4 v[86:89], v200, s[44:47], s22 offen
	v_mfma_f32_32x32x16_bf16 v[50:65], v[208:211], v[224:227], v[50:65]
	s_waitcnt lgkmcnt(7)
	v_mfma_f32_32x32x16_bf16 v[34:49], v[208:211], v[232:235], v[34:49]
	s_waitcnt vmcnt(15)
	ds_write_b128 v199, v[82:85] offset:59904
	buffer_load_dwordx4 v[82:85], v200, s[24:27], s33 offen
	v_mfma_f32_32x32x16_bf16 v[18:33], v[216:219], v[224:227], v[18:33]
	v_mfma_f32_32x32x16_bf16 v[2:17], v[216:219], v[232:235], v[2:17]
	s_add_i32 s22, s0, 0x22000
	ds_read_b128 v[208:211], v138 offset:96
	ds_read_b128 v[216:219], v138 offset:4704
	ds_read_b128 v[224:227], v139 offset:36960
	ds_read_b128 v[232:235], v139 offset:41568
	s_waitcnt vmcnt(15)
	ds_write_b128 v199, v[78:81] offset:27648
	buffer_load_dwordx4 v[78:81], v200, s[44:47], s22 offen
	s_waitcnt lgkmcnt(8)
	v_mfma_f32_32x32x16_bf16 v[50:65], v[204:207], v[220:223], v[50:65]
	s_waitcnt lgkmcnt(7)
	v_mfma_f32_32x32x16_bf16 v[34:49], v[204:207], v[228:231], v[34:49]
	s_waitcnt vmcnt(15)
	ds_write_b128 v199, v[74:77] offset:64512
	buffer_load_dwordx4 v[74:77], v200, s[24:27], s29 offen
	v_mfma_f32_32x32x16_bf16 v[18:33], v[212:215], v[220:223], v[18:33]
	v_mfma_f32_32x32x16_bf16 v[2:17], v[212:215], v[228:231], v[2:17]
	s_add_i32 s22, s0, 0x33000
	s_waitcnt vmcnt(15)
	ds_write_b128 v199, v[70:73] offset:32256
	buffer_load_dwordx4 v[70:73], v200, s[44:47], s22 offen
	s_waitcnt lgkmcnt(4)
	v_mfma_f32_32x32x16_bf16 v[50:65], v[208:211], v[224:227], v[50:65]
	s_waitcnt lgkmcnt(3)
	v_mfma_f32_32x32x16_bf16 v[34:49], v[208:211], v[232:235], v[34:49]
	s_waitcnt vmcnt(15)
	ds_write_b128 v202, v[66:69] offset:13824
	buffer_load_dwordx4 v[66:69], v200, s[24:27], s3 offen
	v_mfma_f32_32x32x16_bf16 v[18:33], v[216:219], v[224:227], v[18:33]
	v_mfma_f32_32x32x16_bf16 v[2:17], v[216:219], v[232:235], v[2:17]
	s_min_u32 s22, s98, 11
	s_lshl_b32 s22, s22, 7
	s_add_i32 s23, s22, 0x200
	s_waitcnt lgkmcnt(0)
	s_barrier
	ds_read_b128 v[204:207], v138 offset:18432
	ds_read_b128 v[208:211], v138 offset:18464
	ds_read_b128 v[212:215], v138 offset:23040
	ds_read_b128 v[216:219], v138 offset:23072
	ds_read_b128 v[220:223], v139 offset:55296
	ds_read_b128 v[224:227], v139 offset:55328
	ds_read_b128 v[228:231], v139 offset:59904
	ds_read_b128 v[232:235], v139 offset:59936
	s_waitcnt vmcnt(15)
	ds_write_b128 v199, v[102:105]
	buffer_load_dwordx4 v[102:105], v200, s[44:47], s23 offen
	s_waitcnt lgkmcnt(4)
	v_mfma_f32_32x32x16_bf16 v[50:65], v[204:207], v[220:223], v[50:65]
	s_add_u32 s24, s56, s23
	s_addc_u32 s23, s2, 0
	s_and_b32 s25, s23, 0xffff
	s_waitcnt lgkmcnt(2)
	v_mfma_f32_32x32x16_bf16 v[34:49], v[204:207], v[228:231], v[34:49]
	s_waitcnt vmcnt(15)
	ds_write_b128 v199, v[98:101] offset:36864
	buffer_load_dwordx4 v[98:101], v200, s[24:27], 0 offen
	v_mfma_f32_32x32x16_bf16 v[18:33], v[212:215], v[220:223], v[18:33]
	v_mfma_f32_32x32x16_bf16 v[2:17], v[212:215], v[228:231], v[2:17]
	s_add_i32 s23, s22, 0x11200
	ds_read_b128 v[204:207], v138 offset:18496
	ds_read_b128 v[212:215], v138 offset:23104
	ds_read_b128 v[220:223], v139 offset:55360
	ds_read_b128 v[228:231], v139 offset:59968
	s_waitcnt vmcnt(15)
	ds_write_b128 v199, v[106:109] offset:4608
	buffer_load_dwordx4 v[106:109], v200, s[44:47], s23 offen
	v_mfma_f32_32x32x16_bf16 v[50:65], v[208:211], v[224:227], v[50:65]
	s_waitcnt lgkmcnt(7)
	v_mfma_f32_32x32x16_bf16 v[34:49], v[208:211], v[232:235], v[34:49]
	s_waitcnt vmcnt(15)
	ds_write_b128 v199, v[110:113] offset:41472
	buffer_load_dwordx4 v[110:113], v200, s[24:27], s33 offen
	v_mfma_f32_32x32x16_bf16 v[18:33], v[216:219], v[224:227], v[18:33]
	v_mfma_f32_32x32x16_bf16 v[2:17], v[216:219], v[232:235], v[2:17]
	s_add_i32 s23, s22, 0x22200
	ds_read_b128 v[208:211], v138 offset:18528
	ds_read_b128 v[216:219], v138 offset:23136
	ds_read_b128 v[224:227], v139 offset:55392
	ds_read_b128 v[232:235], v139 offset:60000
	s_waitcnt vmcnt(15)
	ds_write_b128 v199, v[114:117] offset:9216
	buffer_load_dwordx4 v[114:117], v200, s[44:47], s23 offen
	s_waitcnt lgkmcnt(8)
	v_mfma_f32_32x32x16_bf16 v[50:65], v[204:207], v[220:223], v[50:65]
	s_waitcnt lgkmcnt(7)
	v_mfma_f32_32x32x16_bf16 v[34:49], v[204:207], v[228:231], v[34:49]
	s_waitcnt vmcnt(15)
	ds_write_b128 v199, v[118:121] offset:46080
	buffer_load_dwordx4 v[118:121], v200, s[24:27], s29 offen
	v_mfma_f32_32x32x16_bf16 v[18:33], v[212:215], v[220:223], v[18:33]
	v_mfma_f32_32x32x16_bf16 v[2:17], v[212:215], v[228:231], v[2:17]
	s_add_i32 s22, s22, 0x33200
	s_waitcnt vmcnt(15)
	ds_write_b128 v199, v[122:125] offset:13824
	buffer_load_dwordx4 v[122:125], v200, s[44:47], s22 offen
	s_waitcnt lgkmcnt(4)
	v_mfma_f32_32x32x16_bf16 v[50:65], v[208:211], v[224:227], v[50:65]
	s_waitcnt lgkmcnt(3)
	v_mfma_f32_32x32x16_bf16 v[34:49], v[208:211], v[232:235], v[34:49]
	s_waitcnt vmcnt(15)
	ds_write_b128 v199, v[126:129] offset:50688
	buffer_load_dwordx4 v[126:129], v200, s[24:27], s3 offen
	v_mfma_f32_32x32x16_bf16 v[18:33], v[216:219], v[224:227], v[18:33]
	v_mfma_f32_32x32x16_bf16 v[2:17], v[216:219], v[232:235], v[2:17]
	s_add_i32 s98, s98, 2
	s_add_u32 s0, s0, 0x100
	s_addc_u32 s1, s1, 0
	s_cmp_lt_u32 s98, 14
	s_waitcnt lgkmcnt(0)
	s_barrier
	s_cbranch_scc1 .LBB0_165
	s_waitcnt vmcnt(6)
	ds_read_b128 v[98:101], v138
	ds_read_b128 v[102:105], v139 offset:36864
	s_waitcnt vmcnt(5)
	ds_read_b128 v[106:109], v138 offset:32
	s_waitcnt vmcnt(4)
	ds_read_b128 v[110:113], v139 offset:36896
	s_waitcnt vmcnt(3)
	ds_read_b128 v[114:117], v139 offset:41472
	s_waitcnt vmcnt(2)
	ds_read_b128 v[118:121], v138 offset:4608
	s_waitcnt vmcnt(1)
	ds_read_b128 v[122:125], v138 offset:4640
	s_waitcnt vmcnt(0)
	ds_read_b128 v[126:129], v139 offset:41504
	ds_write_b128 v199, v[94:97] offset:18432
	s_waitcnt lgkmcnt(7)
	v_mfma_f32_32x32x16_bf16 v[50:65], v[98:101], v[102:105], v[50:65]
	s_waitcnt lgkmcnt(4)
	v_mfma_f32_32x32x16_bf16 v[34:49], v[98:101], v[114:117], v[34:49]
	s_waitcnt lgkmcnt(3)
	v_mfma_f32_32x32x16_bf16 v[18:33], v[118:121], v[102:105], v[18:33]
	ds_write_b128 v199, v[90:93] offset:55296
	v_mfma_f32_32x32x16_bf16 v[2:17], v[118:121], v[114:117], v[2:17]
	ds_read_b128 v[90:93], v138 offset:64
	ds_read_b128 v[94:97], v138 offset:4672
	ds_read_b128 v[98:101], v139 offset:36928
	ds_read_b128 v[102:105], v139 offset:41536
	v_mfma_f32_32x32x16_bf16 v[50:65], v[106:109], v[110:113], v[50:65]
	ds_write_b128 v199, v[86:89] offset:23040
	s_waitcnt lgkmcnt(7)
	v_mfma_f32_32x32x16_bf16 v[34:49], v[106:109], v[126:129], v[34:49]
	v_mfma_f32_32x32x16_bf16 v[18:33], v[122:125], v[110:113], v[18:33]
	ds_write_b128 v199, v[82:85] offset:59904
	v_mfma_f32_32x32x16_bf16 v[2:17], v[122:125], v[126:129], v[2:17]
	ds_read_b128 v[82:85], v138 offset:96
	ds_read_b128 v[86:89], v138 offset:4704
	ds_read_b128 v[106:109], v139 offset:36960
	ds_read_b128 v[110:113], v139 offset:41568
	s_waitcnt lgkmcnt(7)
	v_mfma_f32_32x32x16_bf16 v[50:65], v[90:93], v[98:101], v[50:65]
	ds_write_b128 v199, v[78:81] offset:27648
	s_waitcnt lgkmcnt(7)
	v_mfma_f32_32x32x16_bf16 v[34:49], v[90:93], v[102:105], v[34:49]
	v_mfma_f32_32x32x16_bf16 v[18:33], v[94:97], v[98:101], v[18:33]
	ds_write_b128 v199, v[74:77] offset:64512
	v_mfma_f32_32x32x16_bf16 v[2:17], v[94:97], v[102:105], v[2:17]
	s_waitcnt lgkmcnt(3)
	v_mfma_f32_32x32x16_bf16 v[50:65], v[82:85], v[106:109], v[50:65]
	ds_write_b128 v199, v[70:73] offset:32256
	s_waitcnt lgkmcnt(3)
	v_mfma_f32_32x32x16_bf16 v[34:49], v[82:85], v[110:113], v[34:49]
	v_mfma_f32_32x32x16_bf16 v[18:33], v[86:89], v[106:109], v[18:33]
	ds_write_b128 v202, v[66:69] offset:13824
	v_mfma_f32_32x32x16_bf16 v[2:17], v[86:89], v[110:113], v[2:17]
	s_waitcnt lgkmcnt(0)
	s_barrier
	ds_read_b128 v[66:69], v138 offset:18432
	ds_read_b128 v[70:73], v139 offset:55296
	ds_read_b128 v[74:77], v138 offset:18464
	ds_read_b128 v[78:81], v139 offset:55328
	ds_read_b128 v[82:85], v139 offset:59904
	ds_read_b128 v[86:89], v138 offset:23040
	ds_read_b128 v[90:93], v138 offset:23072
	ds_read_b128 v[94:97], v139 offset:59936
	s_waitcnt lgkmcnt(6)
	v_mfma_f32_32x32x16_bf16 v[50:65], v[66:69], v[70:73], v[50:65]
	s_waitcnt lgkmcnt(3)
	v_mfma_f32_32x32x16_bf16 v[34:49], v[66:69], v[82:85], v[34:49]
	s_waitcnt lgkmcnt(2)
	v_mfma_f32_32x32x16_bf16 v[18:33], v[86:89], v[70:73], v[18:33]
	v_mfma_f32_32x32x16_bf16 v[2:17], v[86:89], v[82:85], v[2:17]
	ds_read_b128 v[66:69], v138 offset:18496
	ds_read_b128 v[70:73], v138 offset:23104
	ds_read_b128 v[82:85], v139 offset:55360
	ds_read_b128 v[86:89], v139 offset:59968
	v_mfma_f32_32x32x16_bf16 v[50:65], v[74:77], v[78:81], v[50:65]
	s_waitcnt lgkmcnt(4)
	v_mfma_f32_32x32x16_bf16 v[34:49], v[74:77], v[94:97], v[34:49]
	v_mfma_f32_32x32x16_bf16 v[18:33], v[90:93], v[78:81], v[18:33]
	v_mfma_f32_32x32x16_bf16 v[2:17], v[90:93], v[94:97], v[2:17]
	ds_read_b128 v[74:77], v138 offset:18528
	ds_read_b128 v[78:81], v138 offset:23136
	ds_read_b128 v[90:93], v139 offset:55392
	ds_read_b128 v[94:97], v139 offset:60000
	s_waitcnt lgkmcnt(5)
	v_mfma_f32_32x32x16_bf16 v[50:65], v[66:69], v[82:85], v[50:65]
	s_waitcnt lgkmcnt(4)
	v_mfma_f32_32x32x16_bf16 v[34:49], v[66:69], v[86:89], v[34:49]
	v_mfma_f32_32x32x16_bf16 v[18:33], v[70:73], v[82:85], v[18:33]
	v_mfma_f32_32x32x16_bf16 v[2:17], v[70:73], v[86:89], v[2:17]
	s_waitcnt lgkmcnt(1)
	v_mfma_f32_32x32x16_bf16 v[50:65], v[74:77], v[90:93], v[50:65]
	s_waitcnt lgkmcnt(0)
	v_mfma_f32_32x32x16_bf16 v[34:49], v[74:77], v[94:97], v[34:49]
	v_mfma_f32_32x32x16_bf16 v[18:33], v[78:81], v[90:93], v[18:33]
	v_mfma_f32_32x32x16_bf16 v[2:17], v[78:81], v[94:97], v[2:17]
	v_lshl_or_b32 v66, v198, 2, v201
	s_movk_i32 s0, 0x210
	v_and_or_b32 v67, v137, 64, v151
	v_mul_lo_u32 v66, v66, s0
	v_lshl_add_u32 v66, v67, 2, v66
	s_barrier
	s_nop 3
	ds_write2_b32 v66, v50, v34 offset1:32
	ds_write2_b32 v66, v51, v35 offset0:132 offset1:164
	v_add_u32_e32 v34, 0x400, v66
	ds_write2_b32 v34, v52, v36 offset0:8 offset1:40
	ds_write2_b32 v34, v53, v37 offset0:140 offset1:172
	v_add_u32_e32 v34, 0x1000, v66
	ds_write2_b32 v34, v54, v38 offset0:32 offset1:64
	ds_write2_b32 v34, v55, v39 offset0:164 offset1:196
	v_add_u32_e32 v34, 0x1400, v66
	ds_write2_b32 v34, v56, v40 offset0:40 offset1:72
	ds_write2_b32 v34, v57, v41 offset0:172 offset1:204
	v_add_u32_e32 v34, 0x2000, v66
	ds_write2_b32 v34, v58, v42 offset0:64 offset1:96
	ds_write2_b32 v34, v59, v43 offset0:196 offset1:228
	v_add_u32_e32 v34, 0x2400, v66
	ds_write2_b32 v34, v60, v44 offset0:72 offset1:104
	ds_write2_b32 v34, v61, v45 offset0:204 offset1:236
	v_add_u32_e32 v34, 0x3000, v66
	ds_write2_b32 v34, v62, v46 offset0:96 offset1:128
	v_add_u32_e32 v34, 0x3200, v66
	ds_write2_b32 v34, v63, v47 offset0:100 offset1:132
	v_add_u32_e32 v34, 0x3400, v66
	ds_write2_b32 v34, v64, v48 offset0:104 offset1:136
	v_add_u32_e32 v34, 0x3600, v66
	ds_write2_b32 v34, v65, v49 offset0:108 offset1:140
	v_add_u32_e32 v34, 0x4000, v66
	ds_write2_b32 v34, v18, v2 offset0:128 offset1:160
	v_add_u32_e32 v2, 0x4400, v66
	ds_write2_b32 v2, v19, v3 offset0:4 offset1:36
	ds_write2_b32 v2, v20, v4 offset0:136 offset1:168
	v_add_u32_e32 v2, 0x4800, v66
	ds_write2_b32 v2, v21, v5 offset0:12 offset1:44
	v_add_u32_e32 v2, 0x5000, v66
	ds_write2_b32 v2, v22, v6 offset0:160 offset1:192
	v_add_u32_e32 v2, 0x5400, v66
	ds_write2_b32 v2, v23, v7 offset0:36 offset1:68
	ds_write2_b32 v2, v24, v8 offset0:168 offset1:200
	v_add_u32_e32 v2, 0x5800, v66
	ds_write2_b32 v2, v25, v9 offset0:44 offset1:76
	v_add_u32_e32 v2, 0x6000, v66
	ds_write2_b32 v2, v26, v10 offset0:192 offset1:224
	v_add_u32_e32 v2, 0x6400, v66
	ds_write2_b32 v2, v27, v11 offset0:68 offset1:100
	ds_write2_b32 v2, v28, v12 offset0:200 offset1:232
	v_add_u32_e32 v2, 0x6800, v66
	ds_write2_b32 v2, v29, v13 offset0:76 offset1:108
	v_add_u32_e32 v2, 0x7200, v66
	ds_write2_b32 v2, v30, v14 offset0:96 offset1:128
	v_add_u32_e32 v2, 0x7400, v66
	ds_write2_b32 v2, v31, v15 offset0:100 offset1:132
	v_add_u32_e32 v2, 0x7600, v66
	ds_write2_b32 v2, v32, v16 offset0:104 offset1:136
	v_add_u32_e32 v2, 0x7800, v66
	s_cmp_lg_u32 s96, 0
	s_mov_b64 s[0:1], -1
	ds_write2_b32 v2, v33, v17 offset0:108 offset1:140
	s_waitcnt lgkmcnt(0)
	s_barrier
	ds_write_b32 v140, v135
	s_waitcnt lgkmcnt(0)
	s_barrier
	s_cbranch_scc0 .LBB0_168
	v_add_u32_e32 v2, s55, v141
	v_ashrrev_i32_e32 v3, 31, v2
	v_lshlrev_b64 v[2:3], 11, v[2:3]
	v_lshl_add_u64 v[2:3], s[10:11], 0, v[2:3]
	s_lshl_b32 s96, s51, 1
	v_lshl_add_u64 v[2:3], v[2:3], 0, s[96:97]
	v_mov_b32_e32 v135, v147
	v_or_b32_e32 v13, 0x10a00, v142
	ds_read_b32 v12, v143
	v_lshl_add_u64 v[26:27], v[2:3], 0, v[134:135]
	ds_read_b128 v[2:5], v197
	ds_read_b128 v[6:9], v197 offset:16
	ds_read_b128 v[14:17], v197 offset:32
	ds_read_b128 v[18:21], v197 offset:48
	ds_read_b128 v[22:25], v13
	s_mov_b64 s[0:1], 0x283f800
	v_lshl_add_u64 v[10:11], v[26:27], 0, s[0:1]
	s_waitcnt lgkmcnt(0)
	v_pk_fma_f32 v[2:3], v[2:3], v[12:13], v[22:23] op_sel_hi:[1,0,1]
	s_nop 0
	v_mul_f32_e32 v13, 0xbfb8aa3b, v2
	v_exp_f32_e32 v22, v13
	v_mul_f32_e32 v13, 0xbfb8aa3b, v3
	v_exp_f32_e32 v23, v13
	s_nop 0
	v_pk_add_f32 v[22:23], v[22:23], 1.0 op_sel_hi:[1,0]
	s_nop 0
	v_rcp_f32_e32 v28, v23
	s_nop 0
	v_mul_f32_e32 v30, v3, v28
	v_fma_f32 v31, -v23, v30, v3
	v_fma_f32 v13, v31, v28, v30
	v_div_fixup_f32 v3, v13, v23, v3
	v_rcp_f32_e32 v23, v22
	s_nop 0
	v_mul_f32_e32 v29, v2, v23
	v_fma_f32 v30, -v22, v29, v2
	v_fma_f32 v13, v30, v23, v29
	v_div_fixup_f32 v2, v13, v22, v2
	v_pk_fma_f32 v[4:5], v[4:5], v[12:13], v[24:25] op_sel_hi:[1,0,1]
	v_cvt_pk_bf16_f32 v2, v2, v3
	v_mul_f32_e32 v3, 0xbfb8aa3b, v4
	v_exp_f32_e32 v22, v3
	v_mul_f32_e32 v3, 0xbfb8aa3b, v5
	v_exp_f32_e32 v23, v3
	s_nop 0
	v_pk_add_f32 v[22:23], v[22:23], 1.0 op_sel_hi:[1,0]
	s_nop 0
	v_rcp_f32_e32 v13, v23
	s_nop 0
	v_mul_f32_e32 v25, v5, v13
	v_fma_f32 v28, -v23, v25, v5
	v_fma_f32 v3, v28, v13, v25
	v_div_fixup_f32 v3, v3, v23, v5
	v_rcp_f32_e32 v13, v22
	s_nop 0
	v_mul_f32_e32 v24, v4, v13
	v_fma_f32 v25, -v22, v24, v4
	v_fma_f32 v5, v25, v13, v24
	v_div_fixup_f32 v4, v5, v22, v4
	v_cvt_pk_bf16_f32 v3, v4, v3
	v_add_u32_e32 v4, 0x10a10, v142
	ds_read_b128 v[22:25], v4
	s_waitcnt lgkmcnt(0)
	v_pk_fma_f32 v[4:5], v[6:7], v[12:13], v[22:23] op_sel_hi:[1,0,1]
	s_nop 0
	v_mul_f32_e32 v6, 0xbfb8aa3b, v4
	v_mul_f32_e32 v7, 0xbfb8aa3b, v5
	v_exp_f32_e32 v6, v6
	v_exp_f32_e32 v7, v7
	s_nop 0
	v_pk_add_f32 v[6:7], v[6:7], 1.0 op_sel_hi:[1,0]
	s_nop 0
	v_rcp_f32_e32 v22, v7
	s_nop 0
	v_mul_f32_e32 v28, v5, v22
	v_fma_f32 v29, -v7, v28, v5
	v_fma_f32 v13, v29, v22, v28
	v_div_fixup_f32 v5, v13, v7, v5
	v_rcp_f32_e32 v13, v6
	s_nop 0
	v_mul_f32_e32 v23, v4, v13
	v_fma_f32 v28, -v6, v23, v4
	v_fma_f32 v7, v28, v13, v23
	v_div_fixup_f32 v4, v7, v6, v4
	v_pk_fma_f32 v[6:7], v[8:9], v[12:13], v[24:25] op_sel_hi:[1,0,1]
	v_cvt_pk_bf16_f32 v4, v4, v5
	v_mul_f32_e32 v5, 0xbfb8aa3b, v6
	v_exp_f32_e32 v8, v5
	v_mul_f32_e32 v5, 0xbfb8aa3b, v7
	v_exp_f32_e32 v9, v5
	s_nop 0
	v_pk_add_f32 v[8:9], v[8:9], 1.0 op_sel_hi:[1,0]
	s_nop 0
	v_rcp_f32_e32 v13, v9
	s_nop 0
	v_mul_f32_e32 v23, v7, v13
	v_fma_f32 v24, -v9, v23, v7
	v_fma_f32 v5, v24, v13, v23
	v_div_fixup_f32 v5, v5, v9, v7
	v_div_scale_f32 v7, s[0:1], v8, v8, v6
	v_rcp_f32_e32 v9, v7
	s_mov_b32 s0, 0x283f000
	v_fma_f32 v13, -v7, v9, 1.0
	v_fmac_f32_e32 v9, v13, v9
	v_div_scale_f32 v13, vcc, v6, v8, v6
	v_mul_f32_e32 v22, v13, v9
	v_fma_f32 v23, -v7, v22, v13
	v_fmac_f32_e32 v22, v23, v9
	v_fma_f32 v7, -v7, v22, v13
	v_div_fmas_f32 v7, v7, v9, v22
	v_div_fixup_f32 v6, v7, v8, v6
	v_cvt_pk_bf16_f32 v5, v6, v5
	v_add_co_u32_e32 v6, vcc, s0, v26
	s_nop 1
	v_addc_co_u32_e32 v7, vcc, 0, v27, vcc
	global_store_dwordx4 v[6:7], v[2:5], off offset:2048
	s_nop 1
	v_add_u32_e32 v2, 0x10a20, v142
	ds_read_b128 v[2:5], v2
	s_waitcnt lgkmcnt(0)
	v_pk_fma_f32 v[2:3], v[14:15], v[12:13], v[2:3] op_sel_hi:[1,0,1]
	s_nop 0
	v_mul_f32_e32 v6, 0xbfb8aa3b, v2
	v_mul_f32_e32 v7, 0xbfb8aa3b, v3
	v_exp_f32_e32 v6, v6
	v_exp_f32_e32 v7, v7
	s_nop 0
	v_pk_add_f32 v[6:7], v[6:7], 1.0 op_sel_hi:[1,0]
	s_nop 0
	v_rcp_f32_e32 v9, v7
	s_nop 0
	v_mul_f32_e32 v14, v3, v9
	v_fma_f32 v15, -v7, v14, v3
	v_fma_f32 v8, v15, v9, v14
	v_div_fixup_f32 v3, v8, v7, v3
	v_rcp_f32_e32 v8, v6
	s_nop 0
	v_mul_f32_e32 v13, v2, v8
	v_fma_f32 v14, -v6, v13, v2
	v_fma_f32 v7, v14, v8, v13
	v_div_fixup_f32 v2, v7, v6, v2
	v_pk_fma_f32 v[4:5], v[16:17], v[12:13], v[4:5] op_sel_hi:[1,0,1]
	v_cvt_pk_bf16_f32 v2, v2, v3
	v_mul_f32_e32 v3, 0xbfb8aa3b, v4
	v_exp_f32_e32 v6, v3
	v_mul_f32_e32 v3, 0xbfb8aa3b, v5
	v_exp_f32_e32 v7, v3
	s_nop 0
	v_pk_add_f32 v[6:7], v[6:7], 1.0 op_sel_hi:[1,0]
	s_nop 0
	v_rcp_f32_e32 v8, v7
	s_nop 0
	v_mul_f32_e32 v13, v5, v8
	v_fma_f32 v14, -v7, v13, v5
	v_fma_f32 v3, v14, v8, v13
	v_div_fixup_f32 v3, v3, v7, v5
	v_rcp_f32_e32 v7, v6
	s_nop 0
	v_mul_f32_e32 v9, v4, v7
	v_fma_f32 v13, -v6, v9, v4
	v_fma_f32 v5, v13, v7, v9
	v_div_fixup_f32 v4, v5, v6, v4
	v_cvt_pk_bf16_f32 v3, v4, v3
	v_add_u32_e32 v4, 0x10a30, v142
	ds_read_b128 v[4:7], v4
	s_waitcnt lgkmcnt(0)
	v_pk_fma_f32 v[4:5], v[18:19], v[12:13], v[4:5] op_sel_hi:[1,0,1]
	s_nop 0
	v_mul_f32_e32 v8, 0xbfb8aa3b, v4
	v_mul_f32_e32 v9, 0xbfb8aa3b, v5
	v_exp_f32_e32 v8, v8
	v_exp_f32_e32 v9, v9
	s_nop 0
	v_pk_add_f32 v[8:9], v[8:9], 1.0 op_sel_hi:[1,0]
	s_nop 0
	v_rcp_f32_e32 v14, v9
	s_nop 0
	v_mul_f32_e32 v16, v5, v14
	v_fma_f32 v17, -v9, v16, v5
	v_fma_f32 v13, v17, v14, v16
	v_div_fixup_f32 v5, v13, v9, v5
	v_rcp_f32_e32 v13, v8
	s_nop 0
	v_mul_f32_e32 v15, v4, v13
	v_fma_f32 v16, -v8, v15, v4
	v_fma_f32 v9, v16, v13, v15
	v_div_fixup_f32 v4, v9, v8, v4
	v_pk_fma_f32 v[6:7], v[20:21], v[12:13], v[6:7] op_sel_hi:[1,0,1]
	v_cvt_pk_bf16_f32 v4, v4, v5
	v_mul_f32_e32 v5, 0xbfb8aa3b, v6
	v_exp_f32_e32 v8, v5
	v_mul_f32_e32 v5, 0xbfb8aa3b, v7
	v_exp_f32_e32 v9, v5
	s_nop 0
	v_pk_add_f32 v[8:9], v[8:9], 1.0 op_sel_hi:[1,0]
	s_nop 0
	v_rcp_f32_e32 v13, v9
	s_nop 0
	v_mul_f32_e32 v15, v7, v13
	v_fma_f32 v16, -v9, v15, v7
	v_fma_f32 v5, v16, v13, v15
	v_div_fixup_f32 v5, v5, v9, v7
	v_rcp_f32_e32 v9, v8
	s_nop 0
	v_mul_f32_e32 v14, v6, v9
	v_fma_f32 v15, -v8, v14, v6
	v_fma_f32 v7, v15, v9, v14
	v_div_fixup_f32 v6, v7, v8, v6
	v_cvt_pk_bf16_f32 v5, v6, v5
	v_add_u32_e32 v6, 0x10a40, v142
	global_store_dwordx4 v[10:11], v[2:5], off offset:16
	ds_read_b128 v[2:5], v197 offset:64
	ds_read_b128 v[6:9], v6
	s_waitcnt lgkmcnt(0)
	v_pk_fma_f32 v[2:3], v[2:3], v[12:13], v[6:7] op_sel_hi:[1,0,1]
	s_nop 0
	v_mul_f32_e32 v6, 0xbfb8aa3b, v2
	v_mul_f32_e32 v7, 0xbfb8aa3b, v3
	v_exp_f32_e32 v6, v6
	v_exp_f32_e32 v7, v7
	s_nop 0
	v_pk_add_f32 v[6:7], v[6:7], 1.0 op_sel_hi:[1,0]
	s_nop 0
	v_rcp_f32_e32 v14, v7
	s_nop 0
	v_mul_f32_e32 v16, v3, v14
	v_fma_f32 v17, -v7, v16, v3
	v_fma_f32 v13, v17, v14, v16
	v_div_fixup_f32 v3, v13, v7, v3
	v_rcp_f32_e32 v13, v6
	s_nop 0
	v_mul_f32_e32 v15, v2, v13
	v_fma_f32 v16, -v6, v15, v2
	v_fma_f32 v7, v16, v13, v15
	v_div_fixup_f32 v2, v7, v6, v2
	v_pk_fma_f32 v[4:5], v[4:5], v[12:13], v[8:9] op_sel_hi:[1,0,1]
	v_cvt_pk_bf16_f32 v2, v2, v3
	v_mul_f32_e32 v3, 0xbfb8aa3b, v4
	v_exp_f32_e32 v6, v3
	v_mul_f32_e32 v3, 0xbfb8aa3b, v5
	v_exp_f32_e32 v7, v3
	s_nop 0
	v_pk_add_f32 v[6:7], v[6:7], 1.0 op_sel_hi:[1,0]
	s_nop 0
	v_rcp_f32_e32 v8, v7
	s_nop 0
	v_mul_f32_e32 v13, v5, v8
	v_fma_f32 v14, -v7, v13, v5
	v_fma_f32 v3, v14, v8, v13
	v_div_fixup_f32 v3, v3, v7, v5
	v_rcp_f32_e32 v7, v6
	s_nop 0
	v_mul_f32_e32 v9, v4, v7
	v_fma_f32 v13, -v6, v9, v4
	v_fma_f32 v5, v13, v7, v9
	v_div_fixup_f32 v4, v5, v6, v4
	v_add_u32_e32 v8, 0x10a50, v142
	v_cvt_pk_bf16_f32 v3, v4, v3
	ds_read_b128 v[4:7], v197 offset:80
	ds_read_b128 v[14:17], v8
	s_waitcnt lgkmcnt(0)
	v_pk_fma_f32 v[4:5], v[4:5], v[12:13], v[14:15] op_sel_hi:[1,0,1]
	s_nop 0
	v_mul_f32_e32 v8, 0xbfb8aa3b, v4
	v_mul_f32_e32 v9, 0xbfb8aa3b, v5
	v_exp_f32_e32 v8, v8
	v_exp_f32_e32 v9, v9
	s_nop 0
	v_pk_add_f32 v[8:9], v[8:9], 1.0 op_sel_hi:[1,0]
	s_nop 0
	v_rcp_f32_e32 v14, v9
	s_nop 0
	v_mul_f32_e32 v18, v5, v14
	v_fma_f32 v19, -v9, v18, v5
	v_fma_f32 v13, v19, v14, v18
	v_div_fixup_f32 v5, v13, v9, v5
	v_rcp_f32_e32 v13, v8
	s_nop 0
	v_mul_f32_e32 v15, v4, v13
	v_fma_f32 v18, -v8, v15, v4
	v_fma_f32 v9, v18, v13, v15
	v_div_fixup_f32 v4, v9, v8, v4
	v_pk_fma_f32 v[6:7], v[6:7], v[12:13], v[16:17] op_sel_hi:[1,0,1]
	v_cvt_pk_bf16_f32 v4, v4, v5
	v_mul_f32_e32 v5, 0xbfb8aa3b, v6
	v_exp_f32_e32 v8, v5
	v_mul_f32_e32 v5, 0xbfb8aa3b, v7
	v_exp_f32_e32 v9, v5
	s_nop 0
	v_pk_add_f32 v[8:9], v[8:9], 1.0 op_sel_hi:[1,0]
	s_nop 0
	v_rcp_f32_e32 v13, v9
	s_nop 0
	v_mul_f32_e32 v15, v7, v13
	v_fma_f32 v16, -v9, v15, v7
	v_fma_f32 v5, v16, v13, v15
	v_div_fixup_f32 v5, v5, v9, v7
	v_rcp_f32_e32 v9, v8
	s_nop 0
	v_mul_f32_e32 v14, v6, v9
	v_fma_f32 v15, -v8, v14, v6
	v_fma_f32 v7, v15, v9, v14
	v_div_fixup_f32 v6, v7, v8, v6
	v_cvt_pk_bf16_f32 v5, v6, v5
	global_store_dwordx4 v[10:11], v[2:5], off offset:32
	v_add_u32_e32 v13, 0x10a60, v142
	ds_read_b128 v[2:5], v197 offset:96
	ds_read_b128 v[6:9], v197 offset:112
	ds_read_b128 v[14:17], v13
	s_waitcnt lgkmcnt(0)
	v_pk_fma_f32 v[2:3], v[2:3], v[12:13], v[14:15] op_sel_hi:[1,0,1]
	s_nop 0
	v_mul_f32_e32 v13, 0xbfb8aa3b, v2
	v_exp_f32_e32 v14, v13
	v_mul_f32_e32 v13, 0xbfb8aa3b, v3
	v_exp_f32_e32 v15, v13
	s_nop 0
	v_pk_add_f32 v[14:15], v[14:15], 1.0 op_sel_hi:[1,0]
	s_nop 0
	v_rcp_f32_e32 v18, v15
	s_nop 0
	v_mul_f32_e32 v20, v3, v18
	v_fma_f32 v21, -v15, v20, v3
	v_fma_f32 v13, v21, v18, v20
	v_div_fixup_f32 v3, v13, v15, v3
	v_rcp_f32_e32 v15, v14
	s_nop 0
	v_mul_f32_e32 v19, v2, v15
	v_fma_f32 v20, -v14, v19, v2
	v_fma_f32 v13, v20, v15, v19
	v_div_fixup_f32 v2, v13, v14, v2
	v_pk_fma_f32 v[4:5], v[4:5], v[12:13], v[16:17] op_sel_hi:[1,0,1]
	v_cvt_pk_bf16_f32 v2, v2, v3
	v_mul_f32_e32 v3, 0xbfb8aa3b, v4
	v_exp_f32_e32 v14, v3
	v_mul_f32_e32 v3, 0xbfb8aa3b, v5
	v_exp_f32_e32 v15, v3
	s_nop 0
	v_pk_add_f32 v[14:15], v[14:15], 1.0 op_sel_hi:[1,0]
	s_nop 0
	v_rcp_f32_e32 v13, v15
	s_nop 0
	v_mul_f32_e32 v17, v5, v13
	v_fma_f32 v18, -v15, v17, v5
	v_fma_f32 v3, v18, v13, v17
	v_div_fixup_f32 v3, v3, v15, v5
	v_rcp_f32_e32 v13, v14
	s_nop 0
	v_mul_f32_e32 v16, v4, v13
	v_fma_f32 v17, -v14, v16, v4
	v_fma_f32 v5, v17, v13, v16
	v_div_fixup_f32 v4, v5, v14, v4
	v_cvt_pk_bf16_f32 v3, v4, v3
	v_add_u32_e32 v4, 0x10a70, v142
	ds_read_b128 v[14:17], v4
	s_waitcnt lgkmcnt(0)
	v_pk_fma_f32 v[4:5], v[6:7], v[12:13], v[14:15] op_sel_hi:[1,0,1]
	s_nop 0
	v_mul_f32_e32 v6, 0xbfb8aa3b, v4
	v_mul_f32_e32 v7, 0xbfb8aa3b, v5
	v_exp_f32_e32 v6, v6
	v_exp_f32_e32 v7, v7
	s_nop 0
	v_pk_add_f32 v[6:7], v[6:7], 1.0 op_sel_hi:[1,0]
	s_nop 0
	v_rcp_f32_e32 v14, v7
	s_nop 0
	v_mul_f32_e32 v18, v5, v14
	v_fma_f32 v19, -v7, v18, v5
	v_fma_f32 v13, v19, v14, v18
	v_div_fixup_f32 v5, v13, v7, v5
	v_rcp_f32_e32 v13, v6
	s_nop 0
	v_mul_f32_e32 v15, v4, v13
	v_fma_f32 v18, -v6, v15, v4
	v_fma_f32 v7, v18, v13, v15
	v_div_fixup_f32 v4, v7, v6, v4
	v_pk_fma_f32 v[6:7], v[8:9], v[12:13], v[16:17] op_sel_hi:[1,0,1]
	v_cvt_pk_bf16_f32 v4, v4, v5
	v_mul_f32_e32 v5, 0xbfb8aa3b, v6
	v_exp_f32_e32 v8, v5
	v_mul_f32_e32 v5, 0xbfb8aa3b, v7
	v_exp_f32_e32 v9, v5
	s_nop 0
	v_pk_add_f32 v[8:9], v[8:9], 1.0 op_sel_hi:[1,0]
	s_nop 0
	v_rcp_f32_e32 v13, v9
	s_nop 0
	v_mul_f32_e32 v15, v7, v13
	v_fma_f32 v16, -v9, v15, v7
	v_fma_f32 v5, v16, v13, v15
	v_div_fixup_f32 v5, v5, v9, v7
	v_rcp_f32_e32 v9, v8
	s_nop 0
	v_mul_f32_e32 v14, v6, v9
	v_fma_f32 v15, -v8, v14, v6
	v_fma_f32 v7, v15, v9, v14
	v_div_fixup_f32 v6, v7, v8, v6
	v_cvt_pk_bf16_f32 v5, v6, v5
	global_store_dwordx4 v[10:11], v[2:5], off offset:48
	v_add_u32_e32 v13, 0x10a80, v142
	ds_read_b128 v[2:5], v197 offset:128
	ds_read_b128 v[6:9], v197 offset:144
	ds_read_b128 v[14:17], v13
	s_waitcnt lgkmcnt(0)
	v_pk_fma_f32 v[2:3], v[2:3], v[12:13], v[14:15] op_sel_hi:[1,0,1]
	s_nop 0
	v_mul_f32_e32 v13, 0xbfb8aa3b, v2
	v_exp_f32_e32 v14, v13
	v_mul_f32_e32 v13, 0xbfb8aa3b, v3
	v_exp_f32_e32 v15, v13
	s_nop 0
	v_pk_add_f32 v[14:15], v[14:15], 1.0 op_sel_hi:[1,0]
	s_nop 0
	v_rcp_f32_e32 v18, v15
	s_nop 0
	v_mul_f32_e32 v20, v3, v18
	v_fma_f32 v21, -v15, v20, v3
	v_fma_f32 v13, v21, v18, v20
	v_div_fixup_f32 v3, v13, v15, v3
	v_rcp_f32_e32 v15, v14
	s_nop 0
	v_mul_f32_e32 v19, v2, v15
	v_fma_f32 v20, -v14, v19, v2
	v_fma_f32 v13, v20, v15, v19
	v_div_fixup_f32 v2, v13, v14, v2
	v_pk_fma_f32 v[4:5], v[4:5], v[12:13], v[16:17] op_sel_hi:[1,0,1]
	v_cvt_pk_bf16_f32 v2, v2, v3
	v_mul_f32_e32 v3, 0xbfb8aa3b, v4
	v_exp_f32_e32 v14, v3
	v_mul_f32_e32 v3, 0xbfb8aa3b, v5
	v_exp_f32_e32 v15, v3
	s_nop 0
	v_pk_add_f32 v[14:15], v[14:15], 1.0 op_sel_hi:[1,0]
	s_nop 0
	v_rcp_f32_e32 v13, v15
	s_nop 0
	v_mul_f32_e32 v17, v5, v13
	v_fma_f32 v18, -v15, v17, v5
	v_fma_f32 v3, v18, v13, v17
	v_div_fixup_f32 v3, v3, v15, v5
	v_rcp_f32_e32 v13, v14
	s_nop 0
	v_mul_f32_e32 v16, v4, v13
	v_fma_f32 v17, -v14, v16, v4
	v_fma_f32 v5, v17, v13, v16
	v_div_fixup_f32 v4, v5, v14, v4
	v_cvt_pk_bf16_f32 v3, v4, v3
	v_add_u32_e32 v4, 0x10a90, v142
	ds_read_b128 v[14:17], v4
	s_waitcnt lgkmcnt(0)
	v_pk_fma_f32 v[4:5], v[6:7], v[12:13], v[14:15] op_sel_hi:[1,0,1]
	s_nop 0
	v_mul_f32_e32 v6, 0xbfb8aa3b, v4
	v_mul_f32_e32 v7, 0xbfb8aa3b, v5
	v_exp_f32_e32 v6, v6
	v_exp_f32_e32 v7, v7
	s_nop 0
	v_pk_add_f32 v[6:7], v[6:7], 1.0 op_sel_hi:[1,0]
	s_nop 0
	v_rcp_f32_e32 v14, v7
	s_nop 0
	v_mul_f32_e32 v18, v5, v14
	v_fma_f32 v19, -v7, v18, v5
	v_fma_f32 v13, v19, v14, v18
	v_div_fixup_f32 v5, v13, v7, v5
	v_rcp_f32_e32 v13, v6
	s_nop 0
	v_mul_f32_e32 v15, v4, v13
	v_fma_f32 v18, -v6, v15, v4
	v_fma_f32 v7, v18, v13, v15
	v_div_fixup_f32 v4, v7, v6, v4
	v_pk_fma_f32 v[6:7], v[8:9], v[12:13], v[16:17] op_sel_hi:[1,0,1]
	v_cvt_pk_bf16_f32 v4, v4, v5
	v_mul_f32_e32 v5, 0xbfb8aa3b, v6
	v_exp_f32_e32 v8, v5
	v_mul_f32_e32 v5, 0xbfb8aa3b, v7
	v_exp_f32_e32 v9, v5
	s_nop 0
	v_pk_add_f32 v[8:9], v[8:9], 1.0 op_sel_hi:[1,0]
	s_nop 0
	v_rcp_f32_e32 v13, v9
	s_nop 0
	v_mul_f32_e32 v15, v7, v13
	v_fma_f32 v16, -v9, v15, v7
	v_fma_f32 v5, v16, v13, v15
	v_div_fixup_f32 v5, v5, v9, v7
	v_rcp_f32_e32 v9, v8
	s_nop 0
	v_mul_f32_e32 v14, v6, v9
	v_fma_f32 v15, -v8, v14, v6
	v_fma_f32 v7, v15, v9, v14
	v_div_fixup_f32 v6, v7, v8, v6
	v_cvt_pk_bf16_f32 v5, v6, v5
	global_store_dwordx4 v[10:11], v[2:5], off offset:64
	v_add_u32_e32 v13, 0x10aa0, v142
	ds_read_b128 v[2:5], v197 offset:160
	ds_read_b128 v[6:9], v197 offset:176
	ds_read_b128 v[14:17], v13
	s_waitcnt lgkmcnt(0)
	v_pk_fma_f32 v[2:3], v[2:3], v[12:13], v[14:15] op_sel_hi:[1,0,1]
	s_nop 0
	v_mul_f32_e32 v13, 0xbfb8aa3b, v2
	v_exp_f32_e32 v14, v13
	v_mul_f32_e32 v13, 0xbfb8aa3b, v3
	v_exp_f32_e32 v15, v13
	s_nop 0
	v_pk_add_f32 v[14:15], v[14:15], 1.0 op_sel_hi:[1,0]
	s_nop 0
	v_rcp_f32_e32 v18, v15
	s_nop 0
	v_mul_f32_e32 v20, v3, v18
	v_fma_f32 v21, -v15, v20, v3
	v_fma_f32 v13, v21, v18, v20
	v_div_fixup_f32 v3, v13, v15, v3
	v_rcp_f32_e32 v15, v14
	s_nop 0
	v_mul_f32_e32 v19, v2, v15
	v_fma_f32 v20, -v14, v19, v2
	v_fma_f32 v13, v20, v15, v19
	v_div_fixup_f32 v2, v13, v14, v2
	v_pk_fma_f32 v[4:5], v[4:5], v[12:13], v[16:17] op_sel_hi:[1,0,1]
	v_cvt_pk_bf16_f32 v2, v2, v3
	v_mul_f32_e32 v3, 0xbfb8aa3b, v4
	v_exp_f32_e32 v14, v3
	v_mul_f32_e32 v3, 0xbfb8aa3b, v5
	v_exp_f32_e32 v15, v3
	s_nop 0
	v_pk_add_f32 v[14:15], v[14:15], 1.0 op_sel_hi:[1,0]
	s_nop 0
	v_rcp_f32_e32 v13, v15
	s_nop 0
	v_mul_f32_e32 v17, v5, v13
	v_fma_f32 v18, -v15, v17, v5
	v_fma_f32 v3, v18, v13, v17
	v_div_fixup_f32 v3, v3, v15, v5
	v_rcp_f32_e32 v13, v14
	s_nop 0
	v_mul_f32_e32 v16, v4, v13
	v_fma_f32 v17, -v14, v16, v4
	v_fma_f32 v5, v17, v13, v16
	v_div_fixup_f32 v4, v5, v14, v4
	v_cvt_pk_bf16_f32 v3, v4, v3
	v_add_u32_e32 v4, 0x10ab0, v142
	ds_read_b128 v[14:17], v4
	s_waitcnt lgkmcnt(0)
	v_pk_fma_f32 v[4:5], v[6:7], v[12:13], v[14:15] op_sel_hi:[1,0,1]
	s_nop 0
	v_mul_f32_e32 v6, 0xbfb8aa3b, v4
	v_mul_f32_e32 v7, 0xbfb8aa3b, v5
	v_exp_f32_e32 v6, v6
	v_exp_f32_e32 v7, v7
	s_nop 0
	v_pk_add_f32 v[6:7], v[6:7], 1.0 op_sel_hi:[1,0]
	s_nop 0
	v_rcp_f32_e32 v14, v7
	s_nop 0
	v_mul_f32_e32 v18, v5, v14
	v_fma_f32 v19, -v7, v18, v5
	v_fma_f32 v13, v19, v14, v18
	v_div_fixup_f32 v5, v13, v7, v5
	v_rcp_f32_e32 v13, v6
	s_nop 0
	v_mul_f32_e32 v15, v4, v13
	v_fma_f32 v18, -v6, v15, v4
	v_fma_f32 v7, v18, v13, v15
	v_div_fixup_f32 v4, v7, v6, v4
	v_pk_fma_f32 v[6:7], v[8:9], v[12:13], v[16:17] op_sel_hi:[1,0,1]
	v_cvt_pk_bf16_f32 v4, v4, v5
	v_mul_f32_e32 v5, 0xbfb8aa3b, v6
	v_exp_f32_e32 v8, v5
	v_mul_f32_e32 v5, 0xbfb8aa3b, v7
	v_exp_f32_e32 v9, v5
	s_nop 0
	v_pk_add_f32 v[8:9], v[8:9], 1.0 op_sel_hi:[1,0]
	s_nop 0
	v_rcp_f32_e32 v13, v9
	s_nop 0
	v_mul_f32_e32 v15, v7, v13
	v_fma_f32 v16, -v9, v15, v7
	v_fma_f32 v5, v16, v13, v15
	v_div_fixup_f32 v5, v5, v9, v7
	v_rcp_f32_e32 v9, v8
	s_nop 0
	v_mul_f32_e32 v14, v6, v9
	v_fma_f32 v15, -v8, v14, v6
	v_fma_f32 v7, v15, v9, v14
	v_div_fixup_f32 v6, v7, v8, v6
	v_cvt_pk_bf16_f32 v5, v6, v5
	global_store_dwordx4 v[10:11], v[2:5], off offset:80
	v_add_u32_e32 v13, 0x10ac0, v142
	ds_read_b128 v[2:5], v197 offset:192
	ds_read_b128 v[6:9], v197 offset:208
	ds_read_b128 v[14:17], v13
	s_waitcnt lgkmcnt(0)
	v_pk_fma_f32 v[2:3], v[2:3], v[12:13], v[14:15] op_sel_hi:[1,0,1]
	s_nop 0
	v_mul_f32_e32 v13, 0xbfb8aa3b, v2
	v_exp_f32_e32 v14, v13
	v_mul_f32_e32 v13, 0xbfb8aa3b, v3
	v_exp_f32_e32 v15, v13
	s_nop 0
	v_pk_add_f32 v[14:15], v[14:15], 1.0 op_sel_hi:[1,0]
	s_nop 0
	v_rcp_f32_e32 v18, v15
	s_nop 0
	v_mul_f32_e32 v20, v3, v18
	v_fma_f32 v21, -v15, v20, v3
	v_fma_f32 v13, v21, v18, v20
	v_div_fixup_f32 v3, v13, v15, v3
	v_rcp_f32_e32 v15, v14
	s_nop 0
	v_mul_f32_e32 v19, v2, v15
	v_fma_f32 v20, -v14, v19, v2
	v_fma_f32 v13, v20, v15, v19
	v_div_fixup_f32 v2, v13, v14, v2
	v_pk_fma_f32 v[4:5], v[4:5], v[12:13], v[16:17] op_sel_hi:[1,0,1]
	v_cvt_pk_bf16_f32 v2, v2, v3
	v_mul_f32_e32 v3, 0xbfb8aa3b, v4
	v_exp_f32_e32 v14, v3
	v_mul_f32_e32 v3, 0xbfb8aa3b, v5
	v_exp_f32_e32 v15, v3
	s_nop 0
	v_pk_add_f32 v[14:15], v[14:15], 1.0 op_sel_hi:[1,0]
	s_nop 0
	v_rcp_f32_e32 v13, v15
	s_nop 0
	v_mul_f32_e32 v17, v5, v13
	v_fma_f32 v18, -v15, v17, v5
	v_fma_f32 v3, v18, v13, v17
	v_div_fixup_f32 v3, v3, v15, v5
	v_rcp_f32_e32 v13, v14
	s_nop 0
	v_mul_f32_e32 v16, v4, v13
	v_fma_f32 v17, -v14, v16, v4
	v_fma_f32 v5, v17, v13, v16
	v_div_fixup_f32 v4, v5, v14, v4
	v_cvt_pk_bf16_f32 v3, v4, v3
	v_add_u32_e32 v4, 0x10ad0, v142
	ds_read_b128 v[14:17], v4
	s_waitcnt lgkmcnt(0)
	v_pk_fma_f32 v[4:5], v[6:7], v[12:13], v[14:15] op_sel_hi:[1,0,1]
	s_nop 0
	v_mul_f32_e32 v6, 0xbfb8aa3b, v4
	v_mul_f32_e32 v7, 0xbfb8aa3b, v5
	v_exp_f32_e32 v6, v6
	v_exp_f32_e32 v7, v7
	s_nop 0
	v_pk_add_f32 v[6:7], v[6:7], 1.0 op_sel_hi:[1,0]
	s_nop 0
	v_rcp_f32_e32 v14, v7
	s_nop 0
	v_mul_f32_e32 v18, v5, v14
	v_fma_f32 v19, -v7, v18, v5
	v_fma_f32 v13, v19, v14, v18
	v_div_fixup_f32 v5, v13, v7, v5
	v_rcp_f32_e32 v13, v6
	s_nop 0
	v_mul_f32_e32 v15, v4, v13
	v_fma_f32 v18, -v6, v15, v4
	v_fma_f32 v7, v18, v13, v15
	v_div_fixup_f32 v4, v7, v6, v4
	v_pk_fma_f32 v[6:7], v[8:9], v[12:13], v[16:17] op_sel_hi:[1,0,1]
	v_cvt_pk_bf16_f32 v4, v4, v5
	v_mul_f32_e32 v5, 0xbfb8aa3b, v6
	v_exp_f32_e32 v8, v5
	v_mul_f32_e32 v5, 0xbfb8aa3b, v7
	v_exp_f32_e32 v9, v5
	s_nop 0
	v_pk_add_f32 v[8:9], v[8:9], 1.0 op_sel_hi:[1,0]
	s_nop 0
	v_rcp_f32_e32 v13, v9
	s_nop 0
	v_mul_f32_e32 v15, v7, v13
	v_fma_f32 v16, -v9, v15, v7
	v_fma_f32 v5, v16, v13, v15
	v_div_fixup_f32 v5, v5, v9, v7
	v_rcp_f32_e32 v9, v8
	s_nop 0
	v_mul_f32_e32 v14, v6, v9
	v_fma_f32 v15, -v8, v14, v6
	v_fma_f32 v7, v15, v9, v14
	v_div_fixup_f32 v6, v7, v8, v6
	v_cvt_pk_bf16_f32 v5, v6, v5
	global_store_dwordx4 v[10:11], v[2:5], off offset:96
	v_add_u32_e32 v13, 0x10ae0, v142
	ds_read_b128 v[2:5], v197 offset:224
	ds_read_b128 v[6:9], v197 offset:240
	ds_read_b128 v[14:17], v13
	s_waitcnt lgkmcnt(0)
	v_pk_fma_f32 v[2:3], v[2:3], v[12:13], v[14:15] op_sel_hi:[1,0,1]
	s_nop 0
	v_mul_f32_e32 v13, 0xbfb8aa3b, v2
	v_exp_f32_e32 v14, v13
	v_mul_f32_e32 v13, 0xbfb8aa3b, v3
	v_exp_f32_e32 v15, v13
	s_nop 0
	v_pk_add_f32 v[14:15], v[14:15], 1.0 op_sel_hi:[1,0]
	s_nop 0
	v_rcp_f32_e32 v18, v15
	s_nop 0
	v_mul_f32_e32 v20, v3, v18
	v_fma_f32 v21, -v15, v20, v3
	v_fma_f32 v13, v21, v18, v20
	v_div_fixup_f32 v3, v13, v15, v3
	v_rcp_f32_e32 v15, v14
	s_nop 0
	v_mul_f32_e32 v19, v2, v15
	v_fma_f32 v20, -v14, v19, v2
	v_fma_f32 v13, v20, v15, v19
	v_div_fixup_f32 v2, v13, v14, v2
	v_pk_fma_f32 v[4:5], v[4:5], v[12:13], v[16:17] op_sel_hi:[1,0,1]
	v_cvt_pk_bf16_f32 v2, v2, v3
	v_mul_f32_e32 v3, 0xbfb8aa3b, v4
	v_exp_f32_e32 v14, v3
	v_mul_f32_e32 v3, 0xbfb8aa3b, v5
	v_exp_f32_e32 v15, v3
	s_nop 0
	v_pk_add_f32 v[14:15], v[14:15], 1.0 op_sel_hi:[1,0]
	s_nop 0
	v_rcp_f32_e32 v13, v15
	s_nop 0
	v_mul_f32_e32 v17, v5, v13
	v_fma_f32 v18, -v15, v17, v5
	v_fma_f32 v3, v18, v13, v17
	v_div_fixup_f32 v3, v3, v15, v5
	v_rcp_f32_e32 v13, v14
	s_nop 0
	v_mul_f32_e32 v16, v4, v13
	v_fma_f32 v17, -v14, v16, v4
	v_fma_f32 v5, v17, v13, v16
	v_div_fixup_f32 v4, v5, v14, v4
	v_cvt_pk_bf16_f32 v3, v4, v3
	v_add_u32_e32 v4, 0x10af0, v142
	ds_read_b128 v[14:17], v4
	s_waitcnt lgkmcnt(0)
	v_pk_fma_f32 v[4:5], v[6:7], v[12:13], v[14:15] op_sel_hi:[1,0,1]
	s_nop 0
	v_mul_f32_e32 v6, 0xbfb8aa3b, v4
	v_mul_f32_e32 v7, 0xbfb8aa3b, v5
	v_exp_f32_e32 v6, v6
	v_exp_f32_e32 v7, v7
	s_nop 0
	v_pk_add_f32 v[6:7], v[6:7], 1.0 op_sel_hi:[1,0]
	s_nop 0
	v_rcp_f32_e32 v14, v7
	s_nop 0
	v_mul_f32_e32 v18, v5, v14
	v_fma_f32 v19, -v7, v18, v5
	v_fma_f32 v13, v19, v14, v18
	v_div_fixup_f32 v5, v13, v7, v5
	v_rcp_f32_e32 v13, v6
	s_nop 0
	v_mul_f32_e32 v15, v4, v13
	v_fma_f32 v18, -v6, v15, v4
	v_fma_f32 v7, v18, v13, v15
	v_div_fixup_f32 v4, v7, v6, v4
	v_pk_fma_f32 v[6:7], v[8:9], v[12:13], v[16:17] op_sel_hi:[1,0,1]
	v_cvt_pk_bf16_f32 v4, v4, v5
	v_mul_f32_e32 v5, 0xbfb8aa3b, v6
	v_exp_f32_e32 v8, v5
	v_mul_f32_e32 v5, 0xbfb8aa3b, v7
	v_exp_f32_e32 v9, v5
	s_nop 0
	v_pk_add_f32 v[8:9], v[8:9], 1.0 op_sel_hi:[1,0]
	s_nop 0
	v_rcp_f32_e32 v12, v9
	s_nop 0
	v_mul_f32_e32 v14, v7, v12
	v_fma_f32 v15, -v9, v14, v7
	v_fma_f32 v5, v15, v12, v14
	v_div_fixup_f32 v5, v5, v9, v7
	v_div_scale_f32 v7, s[0:1], v8, v8, v6
	v_rcp_f32_e32 v9, v7
	s_mov_b64 s[0:1], 0
	v_fma_f32 v12, -v7, v9, 1.0
	v_fmac_f32_e32 v9, v12, v9
	v_div_scale_f32 v12, vcc, v6, v8, v6
	v_mul_f32_e32 v13, v12, v9
	v_fma_f32 v14, -v7, v13, v12
	v_fmac_f32_e32 v13, v14, v9
	v_fma_f32 v7, -v7, v13, v12
	v_div_fmas_f32 v7, v7, v9, v13
	v_div_fixup_f32 v6, v7, v8, v6
	v_cvt_pk_bf16_f32 v5, v6, v5
	global_store_dwordx4 v[10:11], v[2:5], off offset:112

.LBB0_245:
	s_waitcnt lgkmcnt(14)
	v_mul_f32_e32 v66, 0xbfb8aa3b, v62
	v_mul_f32_e32 v67, 0xbfb8aa3b, v63
	v_exp_f32_e32 v66, v66
	v_exp_f32_e32 v67, v67
	s_nop 0
	v_pk_add_f32 v[66:67], v[66:67], 1.0 op_sel_hi:[1,0]
	s_nop 0
	v_rcp_f32_e32 v69, v67
	s_nop 0
	v_mul_f32_e32 v71, v63, v69
	v_fma_f32 v72, -v67, v71, v63
	v_fma_f32 v68, v72, v69, v71
	v_div_fixup_f32 v63, v68, v67, v63
	v_rcp_f32_e32 v68, v66
	s_nop 0
	v_mul_f32_e32 v70, v62, v68
	v_fma_f32 v71, -v66, v70, v62
	v_fma_f32 v67, v71, v68, v70
	v_div_fixup_f32 v62, v67, v66, v62
	v_mul_f32_e32 v66, 0xbfb8aa3b, v64
	v_mul_f32_e32 v67, 0xbfb8aa3b, v65
	v_exp_f32_e32 v66, v66
	v_exp_f32_e32 v67, v67
	s_nop 0
	v_pk_add_f32 v[66:67], v[66:67], 1.0 op_sel_hi:[1,0]
	s_nop 0
	v_rcp_f32_e32 v69, v67
	s_nop 0
	v_mul_f32_e32 v71, v65, v69
	v_fma_f32 v72, -v67, v71, v65
	v_fma_f32 v68, v72, v69, v71
	v_div_fixup_f32 v65, v68, v67, v65
	v_rcp_f32_e32 v68, v66
	s_nop 0
	v_mul_f32_e32 v70, v64, v68
	v_fma_f32 v71, -v66, v70, v64
	v_fma_f32 v67, v71, v68, v70
	v_div_fixup_f32 v64, v67, v66, v64
	v_mul_f32_e32 v66, 0xbfb8aa3b, v58
	v_mul_f32_e32 v67, 0xbfb8aa3b, v59
	v_exp_f32_e32 v66, v66
	v_exp_f32_e32 v67, v67
	s_nop 0
	v_pk_add_f32 v[66:67], v[66:67], 1.0 op_sel_hi:[1,0]
	s_nop 0
	v_rcp_f32_e32 v69, v67
	s_nop 0
	v_mul_f32_e32 v71, v59, v69
	v_fma_f32 v72, -v67, v71, v59
	v_fma_f32 v68, v72, v69, v71
	v_div_fixup_f32 v59, v68, v67, v59
	v_rcp_f32_e32 v68, v66
	s_nop 0
	v_mul_f32_e32 v70, v58, v68
	v_fma_f32 v71, -v66, v70, v58
	v_fma_f32 v67, v71, v68, v70
	v_div_fixup_f32 v58, v67, v66, v58
	v_mul_f32_e32 v66, 0xbfb8aa3b, v60
	v_mul_f32_e32 v67, 0xbfb8aa3b, v61
	v_exp_f32_e32 v66, v66
	v_exp_f32_e32 v67, v67
	s_nop 0
	v_pk_add_f32 v[66:67], v[66:67], 1.0 op_sel_hi:[1,0]
	s_nop 0
	v_rcp_f32_e32 v69, v67
	s_nop 0
	v_mul_f32_e32 v71, v61, v69
	v_fma_f32 v72, -v67, v71, v61
	v_fma_f32 v68, v72, v69, v71
	v_div_fixup_f32 v61, v68, v67, v61
	v_rcp_f32_e32 v68, v66
	s_nop 0
	v_mul_f32_e32 v70, v60, v68
	v_fma_f32 v71, -v66, v70, v60
	v_fma_f32 v67, v71, v68, v70
	v_div_fixup_f32 v60, v67, v66, v60
	s_waitcnt lgkmcnt(13)
	v_mul_f32_e32 v66, 0xbfb8aa3b, v54
	v_mul_f32_e32 v67, 0xbfb8aa3b, v55
	v_exp_f32_e32 v66, v66
	v_exp_f32_e32 v67, v67
	s_nop 0
	v_pk_add_f32 v[66:67], v[66:67], 1.0 op_sel_hi:[1,0]
	s_nop 0
	v_rcp_f32_e32 v69, v67
	s_nop 0
	v_mul_f32_e32 v71, v55, v69
	v_fma_f32 v72, -v67, v71, v55
	v_fma_f32 v68, v72, v69, v71
	v_div_fixup_f32 v55, v68, v67, v55
	v_rcp_f32_e32 v68, v66
	s_nop 0
	v_mul_f32_e32 v70, v54, v68
	v_fma_f32 v71, -v66, v70, v54
	v_fma_f32 v67, v71, v68, v70
	v_div_fixup_f32 v54, v67, v66, v54
	v_mul_f32_e32 v66, 0xbfb8aa3b, v56
	v_mul_f32_e32 v67, 0xbfb8aa3b, v57
	v_exp_f32_e32 v66, v66
	v_exp_f32_e32 v67, v67
	s_nop 0
	v_pk_add_f32 v[66:67], v[66:67], 1.0 op_sel_hi:[1,0]
	s_nop 0
	v_rcp_f32_e32 v69, v67
	s_nop 0
	v_mul_f32_e32 v71, v57, v69
	v_fma_f32 v72, -v67, v71, v57
	v_fma_f32 v68, v72, v69, v71
	v_div_fixup_f32 v57, v68, v67, v57
	v_rcp_f32_e32 v68, v66
	s_nop 0
	v_mul_f32_e32 v70, v56, v68
	v_fma_f32 v71, -v66, v70, v56
	v_fma_f32 v67, v71, v68, v70
	v_div_fixup_f32 v56, v67, v66, v56
	s_waitcnt lgkmcnt(12)
	v_mul_f32_e32 v66, 0xbfb8aa3b, v50
	v_mul_f32_e32 v67, 0xbfb8aa3b, v51
	v_exp_f32_e32 v66, v66
	v_exp_f32_e32 v67, v67
	s_nop 0
	v_pk_add_f32 v[66:67], v[66:67], 1.0 op_sel_hi:[1,0]
	s_nop 0
	v_rcp_f32_e32 v69, v67
	s_nop 0
	v_mul_f32_e32 v71, v51, v69
	v_fma_f32 v72, -v67, v71, v51
	v_fma_f32 v68, v72, v69, v71
	v_div_fixup_f32 v51, v68, v67, v51
	v_rcp_f32_e32 v68, v66
	s_nop 0
	v_mul_f32_e32 v70, v50, v68
	v_fma_f32 v71, -v66, v70, v50
	v_fma_f32 v67, v71, v68, v70
	v_div_fixup_f32 v50, v67, v66, v50
	v_mul_f32_e32 v66, 0xbfb8aa3b, v52
	v_mul_f32_e32 v67, 0xbfb8aa3b, v53
	v_exp_f32_e32 v66, v66
	v_exp_f32_e32 v67, v67
	s_nop 0
	v_pk_add_f32 v[66:67], v[66:67], 1.0 op_sel_hi:[1,0]
	s_nop 0
	v_rcp_f32_e32 v69, v67
	s_nop 0
	v_mul_f32_e32 v71, v53, v69
	v_fma_f32 v72, -v67, v71, v53
	v_fma_f32 v68, v72, v69, v71
	v_div_fixup_f32 v53, v68, v67, v53
	v_rcp_f32_e32 v68, v66
	s_nop 0
	v_mul_f32_e32 v70, v52, v68
	v_fma_f32 v71, -v66, v70, v52
	v_fma_f32 v67, v71, v68, v70
	v_div_fixup_f32 v52, v67, v66, v52
	s_waitcnt lgkmcnt(11)
	v_mul_f32_e32 v66, 0xbfb8aa3b, v2
	v_mul_f32_e32 v67, 0xbfb8aa3b, v3
	v_exp_f32_e32 v66, v66
	v_exp_f32_e32 v67, v67
	s_nop 0
	v_pk_add_f32 v[66:67], v[66:67], 1.0 op_sel_hi:[1,0]
	s_nop 0
	v_rcp_f32_e32 v69, v67
	s_nop 0
	v_mul_f32_e32 v71, v3, v69
	v_fma_f32 v72, -v67, v71, v3
	v_fma_f32 v68, v72, v69, v71
	v_div_fixup_f32 v3, v68, v67, v3
	v_rcp_f32_e32 v68, v66
	s_nop 0
	v_mul_f32_e32 v70, v2, v68
	v_fma_f32 v71, -v66, v70, v2
	v_fma_f32 v67, v71, v68, v70
	v_div_fixup_f32 v2, v67, v66, v2
	v_mul_f32_e32 v66, 0xbfb8aa3b, v4
	v_mul_f32_e32 v67, 0xbfb8aa3b, v5
	v_exp_f32_e32 v66, v66
	v_exp_f32_e32 v67, v67
	s_nop 0
	v_pk_add_f32 v[66:67], v[66:67], 1.0 op_sel_hi:[1,0]
	s_nop 0
	v_rcp_f32_e32 v69, v67
	s_nop 0
	v_mul_f32_e32 v71, v5, v69
	v_fma_f32 v72, -v67, v71, v5
	v_fma_f32 v68, v72, v69, v71
	v_div_fixup_f32 v5, v68, v67, v5
	v_rcp_f32_e32 v68, v66
	s_nop 0
	v_mul_f32_e32 v70, v4, v68
	v_fma_f32 v71, -v66, v70, v4
	v_fma_f32 v67, v71, v68, v70
	v_div_fixup_f32 v4, v67, v66, v4
	s_waitcnt lgkmcnt(10)
	v_mul_f32_e32 v66, 0xbfb8aa3b, v10
	v_mul_f32_e32 v67, 0xbfb8aa3b, v11
	v_exp_f32_e32 v66, v66
	v_exp_f32_e32 v67, v67
	s_nop 0
	v_pk_add_f32 v[66:67], v[66:67], 1.0 op_sel_hi:[1,0]
	s_nop 0
	v_rcp_f32_e32 v69, v67
	s_nop 0
	v_mul_f32_e32 v71, v11, v69
	v_fma_f32 v72, -v67, v71, v11
	v_fma_f32 v68, v72, v69, v71
	v_div_fixup_f32 v11, v68, v67, v11
	v_rcp_f32_e32 v68, v66
	s_nop 0
	v_mul_f32_e32 v70, v10, v68
	v_fma_f32 v71, -v66, v70, v10
	v_fma_f32 v67, v71, v68, v70
	v_div_fixup_f32 v10, v67, v66, v10
	v_mul_f32_e32 v66, 0xbfb8aa3b, v12
	v_mul_f32_e32 v67, 0xbfb8aa3b, v13
	v_exp_f32_e32 v66, v66
	v_exp_f32_e32 v67, v67
	s_nop 0
	v_pk_add_f32 v[66:67], v[66:67], 1.0 op_sel_hi:[1,0]
	s_nop 0
	v_rcp_f32_e32 v69, v67
	s_nop 0
	v_mul_f32_e32 v71, v13, v69
	v_fma_f32 v72, -v67, v71, v13
	v_fma_f32 v68, v72, v69, v71
	v_div_fixup_f32 v13, v68, v67, v13
	v_rcp_f32_e32 v68, v66
	s_nop 0
	v_mul_f32_e32 v70, v12, v68
	v_fma_f32 v71, -v66, v70, v12
	v_fma_f32 v67, v71, v68, v70
	v_div_fixup_f32 v12, v67, v66, v12
	s_waitcnt lgkmcnt(9)
	v_mul_f32_e32 v66, 0xbfb8aa3b, v14
	v_mul_f32_e32 v67, 0xbfb8aa3b, v15
	v_exp_f32_e32 v66, v66
	v_exp_f32_e32 v67, v67
	s_nop 0
	v_pk_add_f32 v[66:67], v[66:67], 1.0 op_sel_hi:[1,0]
	s_nop 0
	v_rcp_f32_e32 v69, v67
	s_nop 0
	v_mul_f32_e32 v71, v15, v69
	v_fma_f32 v72, -v67, v71, v15
	v_fma_f32 v68, v72, v69, v71
	v_div_fixup_f32 v15, v68, v67, v15
	v_rcp_f32_e32 v68, v66
	s_nop 0
	v_mul_f32_e32 v70, v14, v68
	v_fma_f32 v71, -v66, v70, v14
	v_fma_f32 v67, v71, v68, v70
	v_div_fixup_f32 v14, v67, v66, v14
	v_mul_f32_e32 v66, 0xbfb8aa3b, v16
	v_mul_f32_e32 v67, 0xbfb8aa3b, v17
	v_exp_f32_e32 v66, v66
	v_exp_f32_e32 v67, v67
	s_nop 0
	v_pk_add_f32 v[66:67], v[66:67], 1.0 op_sel_hi:[1,0]
	s_nop 0
	v_rcp_f32_e32 v69, v67
	s_nop 0
	v_mul_f32_e32 v71, v17, v69
	v_fma_f32 v72, -v67, v71, v17
	v_fma_f32 v68, v72, v69, v71
	v_div_fixup_f32 v17, v68, v67, v17
	v_rcp_f32_e32 v68, v66
	s_nop 0
	v_mul_f32_e32 v70, v16, v68
	v_fma_f32 v71, -v66, v70, v16
	v_fma_f32 v67, v71, v68, v70
	v_div_fixup_f32 v16, v67, v66, v16
	s_waitcnt lgkmcnt(8)
	v_mul_f32_e32 v66, 0xbfb8aa3b, v22
	v_mul_f32_e32 v67, 0xbfb8aa3b, v23
	v_exp_f32_e32 v66, v66
	v_exp_f32_e32 v67, v67
	s_nop 0
	v_pk_add_f32 v[66:67], v[66:67], 1.0 op_sel_hi:[1,0]
	s_nop 0
	v_rcp_f32_e32 v69, v67
	s_nop 0
	v_mul_f32_e32 v71, v23, v69
	v_fma_f32 v72, -v67, v71, v23
	v_fma_f32 v68, v72, v69, v71
	v_div_fixup_f32 v23, v68, v67, v23
	v_rcp_f32_e32 v68, v66
	s_nop 0
	v_mul_f32_e32 v70, v22, v68
	v_fma_f32 v71, -v66, v70, v22
	v_fma_f32 v67, v71, v68, v70
	v_div_fixup_f32 v22, v67, v66, v22
	v_mul_f32_e32 v66, 0xbfb8aa3b, v24
	v_mul_f32_e32 v67, 0xbfb8aa3b, v25
	v_exp_f32_e32 v66, v66
	v_exp_f32_e32 v67, v67
	s_nop 0
	v_pk_add_f32 v[66:67], v[66:67], 1.0 op_sel_hi:[1,0]
	s_nop 0
	v_rcp_f32_e32 v69, v67
	s_nop 0
	v_mul_f32_e32 v71, v25, v69
	v_fma_f32 v72, -v67, v71, v25
	v_fma_f32 v68, v72, v69, v71
	v_div_fixup_f32 v25, v68, v67, v25
	v_rcp_f32_e32 v68, v66
	s_nop 0
	v_mul_f32_e32 v70, v24, v68
	v_fma_f32 v71, -v66, v70, v24
	v_fma_f32 v67, v71, v68, v70
	v_div_fixup_f32 v24, v67, v66, v24
	s_waitcnt lgkmcnt(7)
	v_mul_f32_e32 v66, 0xbfb8aa3b, v46
	v_mul_f32_e32 v67, 0xbfb8aa3b, v47
	v_exp_f32_e32 v66, v66
	v_exp_f32_e32 v67, v67
	s_nop 0
	v_pk_add_f32 v[66:67], v[66:67], 1.0 op_sel_hi:[1,0]
	s_nop 0
	v_rcp_f32_e32 v69, v67
	s_nop 0
	v_mul_f32_e32 v71, v47, v69
	v_fma_f32 v72, -v67, v71, v47
	v_fma_f32 v68, v72, v69, v71
	v_div_fixup_f32 v47, v68, v67, v47
	v_rcp_f32_e32 v68, v66
	s_nop 0
	v_mul_f32_e32 v70, v46, v68
	v_fma_f32 v71, -v66, v70, v46
	v_fma_f32 v67, v71, v68, v70
	v_div_fixup_f32 v46, v67, v66, v46
	v_mul_f32_e32 v66, 0xbfb8aa3b, v48
	v_mul_f32_e32 v67, 0xbfb8aa3b, v49
	v_exp_f32_e32 v66, v66
	v_exp_f32_e32 v67, v67
	s_nop 0
	v_pk_add_f32 v[66:67], v[66:67], 1.0 op_sel_hi:[1,0]
	s_nop 0
	v_rcp_f32_e32 v69, v67
	s_nop 0
	v_mul_f32_e32 v71, v49, v69
	v_fma_f32 v72, -v67, v71, v49
	v_fma_f32 v68, v72, v69, v71
	v_div_fixup_f32 v49, v68, v67, v49
	v_rcp_f32_e32 v68, v66
	s_nop 0
	v_mul_f32_e32 v70, v48, v68
	v_fma_f32 v71, -v66, v70, v48
	v_fma_f32 v67, v71, v68, v70
	v_div_fixup_f32 v48, v67, v66, v48
	s_waitcnt lgkmcnt(6)
	v_mul_f32_e32 v66, 0xbfb8aa3b, v42
	v_mul_f32_e32 v67, 0xbfb8aa3b, v43
	v_exp_f32_e32 v66, v66
	v_exp_f32_e32 v67, v67
	s_nop 0
	v_pk_add_f32 v[66:67], v[66:67], 1.0 op_sel_hi:[1,0]
	s_nop 0
	v_rcp_f32_e32 v69, v67
	s_nop 0
	v_mul_f32_e32 v71, v43, v69
	v_fma_f32 v72, -v67, v71, v43
	v_fma_f32 v68, v72, v69, v71
	v_div_fixup_f32 v43, v68, v67, v43
	v_rcp_f32_e32 v68, v66
	s_nop 0
	v_mul_f32_e32 v70, v42, v68
	v_fma_f32 v71, -v66, v70, v42
	v_fma_f32 v67, v71, v68, v70
	v_div_fixup_f32 v42, v67, v66, v42
	v_mul_f32_e32 v66, 0xbfb8aa3b, v44
	v_mul_f32_e32 v67, 0xbfb8aa3b, v45
	v_exp_f32_e32 v66, v66
	v_exp_f32_e32 v67, v67
	s_nop 0
	v_pk_add_f32 v[66:67], v[66:67], 1.0 op_sel_hi:[1,0]
	s_nop 0
	v_rcp_f32_e32 v69, v67
	s_nop 0
	v_mul_f32_e32 v71, v45, v69
	v_fma_f32 v72, -v67, v71, v45
	v_fma_f32 v68, v72, v69, v71
	v_div_fixup_f32 v45, v68, v67, v45
	v_rcp_f32_e32 v68, v66
	s_nop 0
	v_mul_f32_e32 v70, v44, v68
	v_fma_f32 v71, -v66, v70, v44
	v_fma_f32 v67, v71, v68, v70
	v_div_fixup_f32 v44, v67, v66, v44
	s_waitcnt lgkmcnt(3)
	v_mul_f32_e32 v66, 0xbfb8aa3b, v38
	v_mul_f32_e32 v67, 0xbfb8aa3b, v39
	v_exp_f32_e32 v66, v66
	v_exp_f32_e32 v67, v67
	s_nop 0
	v_pk_add_f32 v[66:67], v[66:67], 1.0 op_sel_hi:[1,0]
	s_nop 0
	v_rcp_f32_e32 v69, v67
	s_nop 0
	v_mul_f32_e32 v71, v39, v69
	v_fma_f32 v72, -v67, v71, v39
	v_fma_f32 v68, v72, v69, v71
	v_div_fixup_f32 v39, v68, v67, v39
	v_rcp_f32_e32 v68, v66
	s_nop 0
	v_mul_f32_e32 v70, v38, v68
	v_fma_f32 v71, -v66, v70, v38
	v_fma_f32 v67, v71, v68, v70
	v_div_fixup_f32 v38, v67, v66, v38
	v_mul_f32_e32 v66, 0xbfb8aa3b, v40
	v_mul_f32_e32 v67, 0xbfb8aa3b, v41
	v_exp_f32_e32 v66, v66
	v_exp_f32_e32 v67, v67
	s_nop 0
	v_pk_add_f32 v[66:67], v[66:67], 1.0 op_sel_hi:[1,0]
	s_nop 0
	v_rcp_f32_e32 v69, v67
	s_nop 0
	v_mul_f32_e32 v71, v41, v69
	v_fma_f32 v72, -v67, v71, v41
	v_fma_f32 v68, v72, v69, v71
	v_div_fixup_f32 v41, v68, v67, v41
	v_rcp_f32_e32 v68, v66
	s_nop 0
	v_mul_f32_e32 v70, v40, v68
	v_fma_f32 v71, -v66, v70, v40
	v_fma_f32 v67, v71, v68, v70
	v_div_fixup_f32 v40, v67, v66, v40
	s_waitcnt lgkmcnt(2)
	v_mul_f32_e32 v66, 0xbfb8aa3b, v34
	v_mul_f32_e32 v67, 0xbfb8aa3b, v35
	v_exp_f32_e32 v66, v66
	v_exp_f32_e32 v67, v67
	s_nop 0
	v_pk_add_f32 v[66:67], v[66:67], 1.0 op_sel_hi:[1,0]
	s_nop 0
	v_rcp_f32_e32 v69, v67
	s_nop 0
	v_mul_f32_e32 v71, v35, v69
	v_fma_f32 v72, -v67, v71, v35
	v_fma_f32 v68, v72, v69, v71
	v_div_fixup_f32 v35, v68, v67, v35
	v_rcp_f32_e32 v68, v66
	s_nop 0
	v_mul_f32_e32 v70, v34, v68
	v_fma_f32 v71, -v66, v70, v34
	v_fma_f32 v67, v71, v68, v70
	v_div_fixup_f32 v34, v67, v66, v34
	v_mul_f32_e32 v66, 0xbfb8aa3b, v36
	v_mul_f32_e32 v67, 0xbfb8aa3b, v37
	v_exp_f32_e32 v66, v66
	v_exp_f32_e32 v67, v67
	s_nop 0
	v_pk_add_f32 v[66:67], v[66:67], 1.0 op_sel_hi:[1,0]
	s_nop 0
	v_rcp_f32_e32 v69, v67
	s_nop 0
	v_mul_f32_e32 v71, v37, v69
	v_fma_f32 v72, -v67, v71, v37
	v_fma_f32 v68, v72, v69, v71
	v_div_fixup_f32 v37, v68, v67, v37
	v_rcp_f32_e32 v68, v66
	s_nop 0
	v_mul_f32_e32 v70, v36, v68
	v_fma_f32 v71, -v66, v70, v36
	v_fma_f32 v67, v71, v68, v70
	v_div_fixup_f32 v36, v67, v66, v36
	v_mul_f32_e32 v66, 0xbfb8aa3b, v6
	v_mul_f32_e32 v67, 0xbfb8aa3b, v7
	v_exp_f32_e32 v66, v66
	v_exp_f32_e32 v67, v67
	s_nop 0
	v_pk_add_f32 v[66:67], v[66:67], 1.0 op_sel_hi:[1,0]
	s_nop 0
	v_rcp_f32_e32 v69, v67
	s_nop 0
	v_mul_f32_e32 v71, v7, v69
	v_fma_f32 v72, -v67, v71, v7
	v_fma_f32 v68, v72, v69, v71
	v_div_fixup_f32 v7, v68, v67, v7
	v_rcp_f32_e32 v68, v66
	s_nop 0
	v_mul_f32_e32 v70, v6, v68
	v_fma_f32 v71, -v66, v70, v6
	v_fma_f32 v67, v71, v68, v70
	v_div_fixup_f32 v6, v67, v66, v6
	v_mul_f32_e32 v66, 0xbfb8aa3b, v8
	v_mul_f32_e32 v67, 0xbfb8aa3b, v9
	v_exp_f32_e32 v66, v66
	v_exp_f32_e32 v67, v67
	s_nop 0
	v_pk_add_f32 v[66:67], v[66:67], 1.0 op_sel_hi:[1,0]
	s_nop 0
	v_rcp_f32_e32 v69, v67
	s_nop 0
	v_mul_f32_e32 v71, v9, v69
	v_fma_f32 v72, -v67, v71, v9
	v_fma_f32 v68, v72, v69, v71
	v_div_fixup_f32 v9, v68, v67, v9
	v_rcp_f32_e32 v68, v66
	s_nop 0
	v_mul_f32_e32 v70, v8, v68
	v_fma_f32 v71, -v66, v70, v8
	v_fma_f32 v67, v71, v68, v70
	v_div_fixup_f32 v8, v67, v66, v8
	v_mul_f32_e32 v66, 0xbfb8aa3b, v18
	v_mul_f32_e32 v67, 0xbfb8aa3b, v19
	v_exp_f32_e32 v66, v66
	v_exp_f32_e32 v67, v67
	s_nop 0
	v_pk_add_f32 v[66:67], v[66:67], 1.0 op_sel_hi:[1,0]
	s_nop 0
	v_rcp_f32_e32 v69, v67
	s_nop 0
	v_mul_f32_e32 v71, v19, v69
	v_fma_f32 v72, -v67, v71, v19
	v_fma_f32 v68, v72, v69, v71
	v_div_fixup_f32 v19, v68, v67, v19
	v_rcp_f32_e32 v68, v66
	s_nop 0
	v_mul_f32_e32 v70, v18, v68
	v_fma_f32 v71, -v66, v70, v18
	v_fma_f32 v67, v71, v68, v70
	v_div_fixup_f32 v18, v67, v66, v18
	v_mul_f32_e32 v66, 0xbfb8aa3b, v20
	v_mul_f32_e32 v67, 0xbfb8aa3b, v21
	v_exp_f32_e32 v66, v66
	v_exp_f32_e32 v67, v67
	s_nop 0
	v_pk_add_f32 v[66:67], v[66:67], 1.0 op_sel_hi:[1,0]
	s_nop 0
	v_rcp_f32_e32 v69, v67
	s_nop 0
	v_mul_f32_e32 v71, v21, v69
	v_fma_f32 v72, -v67, v71, v21
	v_fma_f32 v68, v72, v69, v71
	v_div_fixup_f32 v21, v68, v67, v21
	v_rcp_f32_e32 v68, v66
	s_nop 0
	v_mul_f32_e32 v70, v20, v68
	v_fma_f32 v71, -v66, v70, v20
	v_fma_f32 v67, v71, v68, v70
	v_div_fixup_f32 v20, v67, v66, v20
	s_waitcnt lgkmcnt(1)
	v_mul_f32_e32 v66, 0xbfb8aa3b, v26
	v_mul_f32_e32 v67, 0xbfb8aa3b, v27
	v_exp_f32_e32 v66, v66
	v_exp_f32_e32 v67, v67
	s_nop 0
	v_pk_add_f32 v[66:67], v[66:67], 1.0 op_sel_hi:[1,0]
	s_nop 0
	v_rcp_f32_e32 v69, v67
	s_nop 0
	v_mul_f32_e32 v71, v27, v69
	v_fma_f32 v72, -v67, v71, v27
	v_fma_f32 v68, v72, v69, v71
	v_div_fixup_f32 v27, v68, v67, v27
	v_rcp_f32_e32 v68, v66
	s_nop 0
	v_mul_f32_e32 v70, v26, v68
	v_fma_f32 v71, -v66, v70, v26
	v_fma_f32 v67, v71, v68, v70
	v_div_fixup_f32 v26, v67, v66, v26
	v_mul_f32_e32 v66, 0xbfb8aa3b, v28
	v_mul_f32_e32 v67, 0xbfb8aa3b, v29
	v_exp_f32_e32 v66, v66
	v_exp_f32_e32 v67, v67
	s_nop 0
	v_pk_add_f32 v[66:67], v[66:67], 1.0 op_sel_hi:[1,0]
	s_nop 0
	v_rcp_f32_e32 v69, v67
	s_nop 0
	v_mul_f32_e32 v71, v29, v69
	v_fma_f32 v72, -v67, v71, v29
	v_fma_f32 v68, v72, v69, v71
	v_div_fixup_f32 v29, v68, v67, v29
	v_rcp_f32_e32 v68, v66
	s_nop 0
	v_mul_f32_e32 v70, v28, v68
	v_fma_f32 v71, -v66, v70, v28
	v_fma_f32 v67, v71, v68, v70
	v_div_fixup_f32 v28, v67, v66, v28
	s_waitcnt lgkmcnt(0)
	v_mul_f32_e32 v66, 0xbfb8aa3b, v30
	v_mul_f32_e32 v67, 0xbfb8aa3b, v31
	v_exp_f32_e32 v66, v66
	v_exp_f32_e32 v67, v67
	s_nop 0
	v_pk_add_f32 v[66:67], v[66:67], 1.0 op_sel_hi:[1,0]
	s_nop 0
	v_rcp_f32_e32 v69, v67
	s_nop 0
	v_mul_f32_e32 v71, v31, v69
	v_fma_f32 v72, -v67, v71, v31
	v_fma_f32 v68, v72, v69, v71
	v_div_fixup_f32 v31, v68, v67, v31
	v_rcp_f32_e32 v68, v66
	s_nop 0
	v_mul_f32_e32 v70, v30, v68
	v_fma_f32 v71, -v66, v70, v30
	v_fma_f32 v67, v71, v68, v70
	v_div_fixup_f32 v30, v67, v66, v30
	v_mul_f32_e32 v66, 0xbfb8aa3b, v32
	v_mul_f32_e32 v67, 0xbfb8aa3b, v33
	v_exp_f32_e32 v66, v66
	v_exp_f32_e32 v67, v67
	s_nop 0
	v_pk_add_f32 v[66:67], v[66:67], 1.0 op_sel_hi:[1,0]
	s_nop 0
	v_rcp_f32_e32 v69, v67
	s_nop 0
	v_mul_f32_e32 v71, v33, v69
	v_fma_f32 v72, -v67, v71, v33
	v_fma_f32 v68, v72, v69, v71
	v_div_fixup_f32 v33, v68, v67, v33
	v_rcp_f32_e32 v68, v66
	s_nop 0
	v_mul_f32_e32 v70, v32, v68
	v_fma_f32 v71, -v66, v70, v32
	v_fma_f32 v67, v71, v68, v70
	v_div_fixup_f32 v32, v67, v66, v32
	s_or_b64 s[20:21], s[20:21], s[0:1]
	s_andn2_b64 vcc, exec, s[20:21]
	s_mov_b64 s[20:21], -1
	s_cbranch_vccnz .LBB0_243
